# speedup vs baseline: 1.0320x; 1.0044x over previous
.LBB0_85:
	v_mov_b32_e32 v40, v240
	v_mov_b64_e32 v[0:1], s[64:65]
	v_readfirstlane_b32 s17, v40
	s_ashr_i32 s19, s17, 6
	s_and_b32 s18, s19, 3
	s_lshl_b32 s10, s18, 5
	v_and_b32_e32 v6, 31, v40
	s_add_i32 s10, s10, s5
	v_add_u32_e32 v194, s10, v6
	s_movk_i32 s5, 0x5800
	s_lshl_b32 s3, s3, 7
	s_ashr_i32 s20, s17, 8
	v_mad_i64_i32 v[196:197], s[10:11], v194, s5, v[0:1]
	s_and_b32 s3, s3, 0x380
	s_lshl_b32 s90, s3, 1
	s_lshl_b32 s10, s20, 6
	v_bfe_u32 v41, v40, 5, 1
	v_lshl_add_u64 v[2:3], v[196:197], 0, s[90:91]
	s_ashr_i32 s11, s10, 31
	v_lshl_add_u64 v[2:3], s[10:11], 1, v[2:3]
	v_lshlrev_b32_e32 v128, 4, v41
	v_lshl_add_u64 v[2:3], v[2:3], 0, v[128:129]
	global_load_dwordx4 v[130:133], v[2:3], off
	global_load_dwordx4 v[134:137], v[2:3], off offset:32
	global_load_dwordx4 v[138:141], v[2:3], off offset:64
	global_load_dwordx4 v[142:145], v[2:3], off offset:96
	v_bfe_u32 v2, v40, 3, 3
	v_lshl_or_b32 v2, s19, 3, v2
	v_mad_i64_i32 v[0:1], s[10:11], v2, s5, v[0:1]
	v_lshrrev_b32_e32 v3, 1, v2
	s_and_b32 s10, s19, 1
	v_bfe_u32 v2, v40, 2, 4
	v_lshlrev_b32_e32 v6, 7, v6
	v_lshl_or_b32 v2, s10, 5, v2
	v_lshl_or_b32 v43, s20, 13, v6
	v_lshrrev_b32_e32 v6, 1, v40
	v_xor_b32_e32 v7, v3, v40
	v_mul_u32_u24_e32 v2, 0x2c00, v2
	v_bitop3_b32 v6, v41, v6, 7 bitop3:0x78
	v_lshlrev_b32_e32 v128, 1, v2
	v_lshlrev_b32_e32 v4, 3, v40
	v_lshl_or_b32 v204, v6, 4, v43
	v_lshlrev_b32_e32 v6, 4, v7
	s_ashr_i32 s11, s17, 7
	v_lshl_add_u64 v[2:3], s[64:65], 0, v[128:129]
	v_and_b32_e32 v42, 24, v4
	v_lshl_add_u64 v[0:1], v[0:1], 0, s[90:91]
	v_and_b32_e32 v128, 0x70, v6
	v_lshl_or_b32 v4, s11, 5, v42
	s_lshl_b32 s5, s19, 10
	s_lshl_b32 s10, s10, 11
	s_lshl_b32 s11, s11, 12
	v_lshl_add_u64 v[198:199], v[0:1], 0, v[128:129]
	v_lshl_add_u64 v[0:1], v[198:199], 0, s[72:73]
	s_or_b32 s24, s10, s11
	s_add_i32 s19, s5, 0
	s_mov_b32 s10, m0
	s_mov_b32 m0, s19
	s_nop 0
	global_load_lds_dwordx4 v[0:1], off
	s_mov_b32 m0, s10
	v_lshl_add_u64 v[0:1], v[198:199], 0, s[94:95]
	s_add_i32 s21, s19, 0x2000
	s_mov_b32 s10, m0
	s_mov_b32 m0, s21
	s_nop 0
	global_load_lds_dwordx4 v[0:1], off
	s_mov_b32 m0, s10
	s_mov_b64 s[10:11], 0x160800
	v_lshl_add_u64 v[0:1], v[198:199], 0, s[10:11]
	s_add_i32 s10, s19, 0x4000
	s_mov_b32 s11, m0
	s_mov_b32 m0, s10
	s_nop 0
	global_load_lds_dwordx4 v[0:1], off
	s_mov_b32 m0, s11
	s_mov_b64 s[10:11], 0x160880
	v_lshl_add_u64 v[0:1], v[198:199], 0, s[10:11]
	s_add_i32 s10, s19, 0x6000
	s_mov_b32 s11, m0
	s_mov_b32 m0, s10
	s_nop 0
	global_load_lds_dwordx4 v[0:1], off
	s_mov_b32 m0, s11
	s_mov_b64 s[10:11], 0x2c0800
	v_lshl_add_u64 v[0:1], v[198:199], 0, s[10:11]
	s_add_i32 s10, s19, 0x8000
	s_mov_b32 s11, m0
	s_mov_b32 m0, s10
	s_nop 0
	global_load_lds_dwordx4 v[0:1], off
	s_mov_b32 m0, s11
	v_ashrrev_i32_e32 v5, 31, v4
	v_lshl_add_u64 v[2:3], v[2:3], 0, s[90:91]
	s_mov_b64 s[10:11], 0x2c0880
	v_lshl_add_u64 v[2:3], v[4:5], 1, v[2:3]
	v_lshl_add_u64 v[0:1], v[198:199], 0, s[10:11]
	s_add_i32 s10, s19, 0xa000
	s_mov_b32 s11, m0
	s_mov_b32 m0, s10
	s_nop 0
	global_load_lds_dwordx4 v[0:1], off
	s_mov_b32 m0, s11
	s_add_i32 s20, s24, 0
	v_lshl_add_u64 v[200:201], v[2:3], 0, s[98:99]
	s_add_i32 s10, s20, 0x10000
	s_mov_b32 s11, m0
	s_mov_b32 m0, s10
	s_nop 0
	global_load_lds_dwordx4 v[200:201], off
	s_mov_b32 m0, s11
	s_mov_b64 s[10:11], 0x59000
	v_lshl_add_u64 v[0:1], v[2:3], 0, s[10:11]
	s_add_i32 s10, s20, 0x10400
	s_mov_b32 s11, m0
	s_mov_b32 m0, s10
	s_nop 0
	global_load_lds_dwordx4 v[0:1], off
	s_mov_b32 m0, s11
	s_mov_b64 s[10:11], 0x161000
	v_lshl_add_u64 v[0:1], v[2:3], 0, s[10:11]
	s_add_i32 s10, s20, 0x14000
	s_mov_b32 s11, m0
	s_mov_b32 m0, s10
	s_nop 0
	global_load_lds_dwordx4 v[0:1], off
	s_mov_b32 m0, s11
	s_mov_b64 s[10:11], 0x1b9000
	v_lshl_add_u64 v[0:1], v[2:3], 0, s[10:11]
	s_add_i32 s20, s20, 0x14400
	s_mov_b32 s10, m0
	s_mov_b32 m0, s20
	s_nop 0
	global_load_lds_dwordx4 v[0:1], off
	s_mov_b32 m0, s10
	s_waitcnt vmcnt(0)
	s_barrier
	v_add_u32_e32 v44, 0, v204
	ds_read_b128 v[0:3], v44
	ds_read_b128 v[4:7], v44 offset:4096
	s_waitcnt vmcnt(3) lgkmcnt(1)
	v_mfma_f32_32x32x16_bf16 v[16:31], v[0:3], v[130:133], 0
	v_bfe_u32 v45, v40, 1, 3
	v_bitop3_b32 v0, v41, v45, 2 bitop3:0x36
	v_lshl_or_b32 v128, v0, 4, v43
	v_add_u32_e32 v46, 0, v128
	ds_read_b128 v[32:35], v46
	ds_read_b128 v[36:39], v46 offset:4096
	v_lshlrev_b32_e32 v203, 2, v41
	s_mov_b64 s[22:23], 0x420800
	s_waitcnt lgkmcnt(2)
	v_mfma_f32_32x32x16_bf16 v[0:15], v[4:7], v[130:133], 0
	v_mov_b32_e32 v209, 0
	v_and_b32_e32 v202, 63, v40
	v_ashrrev_i32_e32 v195, 31, v194
	s_movk_i32 s10, 0x4000
	s_mov_b32 s11, 0x8000
	s_mov_b32 s20, 0
	s_mov_b32 s33, 0
	s_waitcnt vmcnt(2) lgkmcnt(1)
	v_mfma_f32_32x32x16_bf16 v[16:31], v[32:35], v[134:137], v[16:31]
	v_bitop3_b32 v32, v41, v45, 4 bitop3:0x36
	v_lshl_or_b32 v205, v32, 4, v43
	v_add_u32_e32 v47, 0, v205
	v_mov_b32_e32 v48, 0
	v_mov_b32_e32 v49, v209
	v_mov_b32_e32 v50, v209
	v_mov_b32_e32 v51, v209
	s_waitcnt lgkmcnt(0)
	v_mfma_f32_32x32x16_bf16 v[0:15], v[36:39], v[134:137], v[0:15]
	ds_read_b128 v[32:35], v47
	ds_read_b128 v[36:39], v47 offset:4096
	v_mov_b32_e32 v52, v209
	v_mov_b32_e32 v53, v209
	v_mov_b32_e32 v54, v209
	v_mov_b32_e32 v55, v209
	v_mov_b32_e32 v56, v209
	v_mov_b32_e32 v57, v209
	s_waitcnt vmcnt(1) lgkmcnt(1)
	v_mfma_f32_32x32x16_bf16 v[16:31], v[32:35], v[138:141], v[16:31]
	v_bitop3_b32 v32, v41, v45, 6 bitop3:0x36
	v_lshl_or_b32 v206, v32, 4, v43
	v_add_u32_e32 v43, 0, v206
	ds_read_b128 v[32:35], v43
	v_mov_b32_e32 v45, v209
	v_mov_b32_e32 v58, v209
	v_mov_b32_e32 v59, v209
	s_waitcnt lgkmcnt(1)
	v_mfma_f32_32x32x16_bf16 v[0:15], v[36:39], v[138:141], v[0:15]
	v_lshrrev_b32_e32 v36, 2, v40
	v_and_or_b32 v41, v36, 3, v203
	ds_read_b128 v[36:39], v43 offset:4096
	ds_read_b128 v[100:103], v44 offset:16384
	ds_read_b128 v[96:99], v44 offset:20480
	ds_read_b128 v[182:185], v46 offset:16384
	ds_read_b128 v[178:181], v46 offset:20480
	ds_read_b128 v[174:177], v47 offset:16384
	ds_read_b128 v[170:173], v47 offset:20480
	ds_read_b128 v[166:169], v43 offset:16384
	ds_read_b128 v[162:165], v43 offset:20480
	s_waitcnt lgkmcnt(0)
	s_barrier
	v_mov_b32_e32 v43, v209
	v_mov_b32_e32 v44, v209
	s_waitcnt vmcnt(0) lgkmcnt(9)
	v_mfma_f32_32x32x16_bf16 v[16:31], v[32:35], v[142:145], v[16:31]
	v_lshlrev_b32_e32 v33, 1, v40
	v_lshlrev_b32_e32 v32, 6, v41
	v_and_b32_e32 v33, 32, v33
	v_or3_b32 v207, v32, v33, v42
	v_lshl_add_u64 v[32:33], v[198:199], 0, s[22:23]
	s_mov_b32 s22, m0
	s_add_i32 m0, s19, 0xc000
	s_nop 0
	global_load_lds_dwordx4 v[32:33], off
	s_mov_b32 m0, s22
	s_mov_b64 s[22:23], 0x420880
	s_waitcnt lgkmcnt(8)
	v_mfma_f32_32x32x16_bf16 v[0:15], v[36:39], v[142:145], v[0:15]
	s_nop 3
	v_exp_f32_e32 v80, v16
	v_exp_f32_e32 v81, v17
	v_exp_f32_e32 v82, v18
	v_exp_f32_e32 v83, v19
	v_exp_f32_e32 v84, v20
	v_exp_f32_e32 v85, v21
	v_exp_f32_e32 v86, v22
	v_exp_f32_e32 v87, v23
	v_exp_f32_e32 v88, v24
	v_exp_f32_e32 v89, v25
	v_exp_f32_e32 v90, v26
	v_exp_f32_e32 v91, v27
	v_exp_f32_e32 v92, v28
	v_exp_f32_e32 v93, v29
	v_exp_f32_e32 v94, v30
	v_exp_f32_e32 v95, v31
	v_exp_f32_e32 v64, v0
	v_exp_f32_e32 v65, v1
	v_exp_f32_e32 v66, v2
	v_exp_f32_e32 v67, v3
	v_exp_f32_e32 v68, v4
	v_exp_f32_e32 v69, v5
	v_exp_f32_e32 v70, v6
	v_exp_f32_e32 v71, v7
	v_exp_f32_e32 v72, v8
	v_exp_f32_e32 v73, v9
	v_exp_f32_e32 v74, v10
	v_exp_f32_e32 v75, v11
	v_exp_f32_e32 v76, v12
	v_exp_f32_e32 v77, v13
	v_exp_f32_e32 v78, v14
	v_exp_f32_e32 v79, v15
	v_lshl_add_u64 v[32:33], v[198:199], 0, s[22:23]
	s_mov_b32 s19, m0
	s_add_i32 m0, s21, 0xc000
	s_nop 0
	global_load_lds_dwordx4 v[32:33], off
	s_mov_b32 m0, s19
	v_add_u32_e32 v208, 0, v207
	s_add_i32 s19, s4, -1
	s_add_i32 s21, s5, 0x2000
	s_add_i32 s22, s24, 0x10000
	v_mov_b32_e32 v0, 0
	v_mov_b32_e32 v1, v209
	v_mov_b32_e32 v2, v209
	v_mov_b32_e32 v3, v209
	v_mov_b32_e32 v4, v209
	v_mov_b32_e32 v5, v209
	v_mov_b32_e32 v6, v209
	v_mov_b32_e32 v7, v209
	v_mov_b32_e32 v8, v209
	v_mov_b32_e32 v9, v209
	v_mov_b32_e32 v10, v209
	v_mov_b32_e32 v11, v209
	v_mov_b32_e32 v12, v209
	v_mov_b32_e32 v13, v209
	v_mov_b32_e32 v14, v209
	v_mov_b32_e32 v15, v209
	v_mov_b32_e32 v16, 0
	v_mov_b32_e32 v17, v209
	v_mov_b32_e32 v18, v209
	v_mov_b32_e32 v19, v209
	v_mov_b32_e32 v20, v209
	v_mov_b32_e32 v21, v209
	v_mov_b32_e32 v22, v209
	v_mov_b32_e32 v23, v209
	v_mov_b32_e32 v24, v209
	v_mov_b32_e32 v25, v209
	v_mov_b32_e32 v26, v209
	v_mov_b32_e32 v27, v209
	v_mov_b32_e32 v28, v209
	v_mov_b32_e32 v29, v209
	v_mov_b32_e32 v30, v209
	v_mov_b32_e32 v31, v209
	v_mov_b32_e32 v32, 0
	v_mov_b32_e32 v33, v209
	v_mov_b32_e32 v34, v209
	v_mov_b32_e32 v35, v209
	v_mov_b32_e32 v36, v209
	v_mov_b32_e32 v37, v209
	v_mov_b32_e32 v38, v209
	v_mov_b32_e32 v39, v209
	v_mov_b32_e32 v40, v209
	v_mov_b32_e32 v41, v209
	v_mov_b32_e32 v42, v209
	v_mov_b32_e32 v46, v209
	v_mov_b32_e32 v47, v209
	v_mov_b32_e32 v60, v209
	v_mov_b32_e32 v61, v209
	v_mov_b32_e32 v62, v209
	v_mov_b32_e32 v63, v209
	v_readfirstlane_b32 s44, v198
	v_readfirstlane_b32 s45, v199
	s_nop 1
	s_sub_u32 s44, s44, 0x200000
	s_subb_u32 s45, s45, 0
	s_add_i32 s32, s21, 0xffffff80
	v_subrev_u32_e32 v199, s44, v198
	v_add_u32_e32 v199, 0x800, v199
	v_subrev_u32_e32 v201, s44, v200
	s_min_u32 s90, s19, 4
	s_mul_i32 s90, s90, 0x160000
	s_add_i32 m0, s5, 0
	s_add_u32 s100, s44, s90
	s_addc_u32 s101, s45, 0
	global_load_lds_dwordx4 v199, s[100:101]
	s_add_i32 m0, s32, 0
	s_nop 0
	global_load_lds_dwordx4 v199, s[100:101] offset:128
	s_mov_b32 s90, 0x2c0000
	s_add_i32 m0, s22, 0x8000
	s_add_u32 s100, s44, s90
	s_addc_u32 s101, s45, 0
	global_load_lds_dwordx4 v201, s[100:101]
	s_add_i32 m0, s22, 0x8400
	s_add_u32 s100, s100, 0x58000
	s_addc_u32 s101, s101, 0
	global_load_lds_dwordx4 v201, s[100:101]
	v_add_u32_e32 v207, 0x10000, v207
.LBB0_86:
	s_add_i32 s24, s33, 2
	v_mfma_f32_32x32x16_bf16 v[112:127], v[100:103], v[130:133], 0
	v_add_f32_e32 v100, v82, v80
	v_add_f32_e32 v101, v83, v81
	v_cvt_pk_bf16_f32 v158, v80, v81
	v_cvt_pk_bf16_f32 v159, v82, v83
	v_add_f32_e32 v80, v84, v100
	v_add_f32_e32 v81, v85, v101
	v_add_f32_e32 v146, v86, v80
	v_cvt_pk_bf16_f32 v160, v84, v85
	v_mfma_f32_32x32x16_bf16 v[96:111], v[96:99], v[130:133], 0
	v_add_f32_e32 v84, v87, v81
	v_cvt_pk_bf16_f32 v161, v86, v87
	ds_read_b64_tr_b16 v[80:81], v207
	ds_read_b64_tr_b16 v[82:83], v207 offset:512
	v_add_f32_e32 v85, v88, v146
	v_add_f32_e32 v84, v89, v84
	v_mfma_f32_32x32x16_bf16 v[112:127], v[182:185], v[134:137], v[112:127]
	v_add_f32_e32 v146, v90, v85
	v_add_f32_e32 v147, v91, v84
	v_cvt_pk_bf16_f32 v154, v88, v89
	v_cvt_pk_bf16_f32 v155, v90, v91
	ds_read_b64_tr_b16 v[84:85], v207 offset:4096
	ds_read_b64_tr_b16 v[86:87], v207 offset:4608
	v_add_f32_e32 v88, v92, v146
	v_add_f32_e32 v89, v93, v147
	v_mfma_f32_32x32x16_bf16 v[96:111], v[178:181], v[134:137], v[96:111]
	v_add_f32_e32 v146, v94, v88
	v_add_f32_e32 v147, v95, v89
	v_cvt_pk_bf16_f32 v156, v92, v93
	v_cvt_pk_bf16_f32 v157, v94, v95
	ds_read_b64_tr_b16 v[88:89], v207 offset:8192
	ds_read_b64_tr_b16 v[90:91], v207 offset:8704
	v_add_f32_e32 v92, v64, v146
	v_add_f32_e32 v93, v65, v147
	v_mfma_f32_32x32x16_bf16 v[112:127], v[174:177], v[138:141], v[112:127]
	v_add_f32_e32 v92, v66, v92
	v_add_f32_e32 v93, v67, v93
	v_cvt_pk_bf16_f32 v150, v64, v65
	v_cvt_pk_bf16_f32 v151, v66, v67
	ds_read_b64_tr_b16 v[64:65], v207 offset:12288
	ds_read_b64_tr_b16 v[66:67], v207 offset:12800
	v_add_f32_e32 v92, v68, v92
	v_add_f32_e32 v93, v69, v93
	v_mfma_f32_32x32x16_bf16 v[96:111], v[170:173], v[138:141], v[96:111]
	s_add_i32 s90, s33, 5
	s_min_u32 s90, s90, s19
	s_mul_i32 s90, s90, 0x160000
	s_add_i32 m0, s5, 0x4000
	s_add_u32 s100, s44, s90
	s_addc_u32 s101, s45, 0
	global_load_lds_dwordx4 v199, s[100:101]
	v_add_f32_e32 v92, v70, v92
	v_add_f32_e32 v93, v71, v93
	v_cvt_pk_bf16_f32 v152, v68, v69
	v_cvt_pk_bf16_f32 v153, v70, v71
	v_add_f32_e32 v68, v72, v92
	v_add_f32_e32 v69, v73, v93
	v_mfma_f32_32x32x16_bf16 v[112:127], v[166:169], v[142:145], v[112:127]
	s_add_i32 m0, s32, 0x4000
	s_nop 0
	global_load_lds_dwordx4 v199, s[100:101] offset:128
	v_add_f32_e32 v68, v74, v68
	v_add_f32_e32 v69, v75, v69
	v_cvt_pk_bf16_f32 v146, v72, v73
	v_cvt_pk_bf16_f32 v147, v74, v75
	v_add_f32_e32 v68, v76, v68
	v_add_f32_e32 v69, v77, v69
	v_mfma_f32_32x32x16_bf16 v[96:111], v[162:165], v[142:145], v[96:111]
	s_add_i32 s90, s33, 3
	s_min_u32 s90, s90, s19
	s_mul_i32 s90, s90, 0x160000
	s_add_i32 m0, s22, 0xc000
	s_add_u32 s100, s44, s90
	s_addc_u32 s101, s45, 0
	global_load_lds_dwordx4 v201, s[100:101]
	v_add_f32_e32 v68, v78, v68
	v_add_f32_e32 v69, v79, v69
	v_cvt_pk_bf16_f32 v148, v76, v77
	v_cvt_pk_bf16_f32 v149, v78, v79
	s_nop 0
	v_exp_f32_e32 v112, v112
	v_exp_f32_e32 v113, v113
	s_waitcnt lgkmcnt(4)
	v_mfma_f32_32x32x16_bf16 v[48:63], v[80:83], v[158:161], v[48:63]
	v_add_f32_e32 v92, v68, v69
	ds_read_b64_tr_b16 v[68:69], v207 offset:1024
	ds_read_b64_tr_b16 v[70:71], v207 offset:1536
	v_exp_f32_e32 v114, v114
	v_exp_f32_e32 v115, v115
	v_mfma_f32_32x32x16_bf16 v[32:47], v[84:87], v[158:161], v[32:47]
	ds_read_b64_tr_b16 v[72:73], v207 offset:5120
	ds_read_b64_tr_b16 v[74:75], v207 offset:5632
	v_exp_f32_e32 v116, v116
	v_exp_f32_e32 v117, v117
	s_waitcnt lgkmcnt(4)
	v_mfma_f32_32x32x16_bf16 v[16:31], v[88:91], v[158:161], v[16:31]
	ds_read_b64_tr_b16 v[76:77], v207 offset:9216
	ds_read_b64_tr_b16 v[78:79], v207 offset:9728
	v_exp_f32_e32 v118, v118
	v_exp_f32_e32 v119, v119
	v_mfma_f32_32x32x16_bf16 v[0:15], v[64:67], v[158:161], v[0:15]
	ds_read_b64_tr_b16 v[80:81], v207 offset:13312
	ds_read_b64_tr_b16 v[82:83], v207 offset:13824
	v_exp_f32_e32 v120, v120
	v_exp_f32_e32 v121, v121
	s_waitcnt lgkmcnt(4)
	v_mfma_f32_32x32x16_bf16 v[48:63], v[68:71], v[154:157], v[48:63]
	ds_read_b64_tr_b16 v[84:85], v207 offset:2048
	ds_read_b64_tr_b16 v[86:87], v207 offset:2560
	ds_read_b128 v[68:71], v204 offset:32768
	v_exp_f32_e32 v122, v122
	v_exp_f32_e32 v123, v123
	v_mfma_f32_32x32x16_bf16 v[32:47], v[72:75], v[154:157], v[32:47]
	ds_read_b64_tr_b16 v[72:73], v207 offset:6144
	ds_read_b64_tr_b16 v[74:75], v207 offset:6656
	ds_read_b128 v[64:67], v204 offset:36864
	v_exp_f32_e32 v124, v124
	v_exp_f32_e32 v125, v125
	s_waitcnt lgkmcnt(6)
	v_mfma_f32_32x32x16_bf16 v[16:31], v[76:79], v[154:157], v[16:31]
	ds_read_b64_tr_b16 v[76:77], v207 offset:10240
	ds_read_b64_tr_b16 v[78:79], v207 offset:10752
	ds_read_b128 v[182:185], v128 offset:32768
	v_exp_f32_e32 v126, v126
	v_exp_f32_e32 v127, v127
	v_mfma_f32_32x32x16_bf16 v[0:15], v[80:83], v[154:157], v[0:15]
	ds_read_b64_tr_b16 v[80:81], v207 offset:14336
	ds_read_b64_tr_b16 v[82:83], v207 offset:14848
	ds_read_b128 v[178:181], v128 offset:36864
	v_exp_f32_e32 v96, v96
	v_exp_f32_e32 v97, v97
	s_waitcnt lgkmcnt(7)
	v_mfma_f32_32x32x16_bf16 v[48:63], v[84:87], v[150:153], v[48:63]
	ds_read_b64_tr_b16 v[84:85], v207 offset:3072
	ds_read_b64_tr_b16 v[86:87], v207 offset:3584
	ds_read_b128 v[174:177], v205 offset:32768
	v_exp_f32_e32 v98, v98
	v_exp_f32_e32 v99, v99
	v_mfma_f32_32x32x16_bf16 v[32:47], v[72:75], v[150:153], v[32:47]
	ds_read_b64_tr_b16 v[72:73], v207 offset:7168
	ds_read_b64_tr_b16 v[74:75], v207 offset:7680
	ds_read_b128 v[170:173], v205 offset:36864
	v_exp_f32_e32 v100, v100
	v_exp_f32_e32 v101, v101
	s_waitcnt lgkmcnt(7)
	v_mfma_f32_32x32x16_bf16 v[16:31], v[76:79], v[150:153], v[16:31]
	ds_read_b64_tr_b16 v[76:77], v207 offset:11264
	ds_read_b64_tr_b16 v[78:79], v207 offset:11776
	ds_read_b128 v[166:169], v206 offset:32768
	v_exp_f32_e32 v102, v102
	v_exp_f32_e32 v103, v103
	v_mfma_f32_32x32x16_bf16 v[0:15], v[80:83], v[150:153], v[0:15]
	ds_read_b64_tr_b16 v[80:81], v207 offset:15360
	ds_read_b64_tr_b16 v[82:83], v207 offset:15872
	ds_read_b128 v[162:165], v206 offset:36864
	v_exp_f32_e32 v104, v104
	v_exp_f32_e32 v105, v105
	s_waitcnt lgkmcnt(7)
	v_mfma_f32_32x32x16_bf16 v[48:63], v[84:87], v[146:149], v[48:63]
	s_add_i32 m0, s22, 0xc000
	s_addk_i32 m0, 0x400
	s_add_u32 s100, s100, 0x58000
	s_addc_u32 s101, s101, 0
	global_load_lds_dwordx4 v201, s[100:101]
	v_exp_f32_e32 v106, v106
	v_exp_f32_e32 v107, v107
	v_mfma_f32_32x32x16_bf16 v[32:47], v[72:75], v[146:149], v[32:47]
	v_exp_f32_e32 v108, v108
	v_exp_f32_e32 v109, v109
	s_waitcnt lgkmcnt(1)
	v_mfma_f32_32x32x16_bf16 v[16:31], v[76:79], v[146:149], v[16:31]
	v_exp_f32_e32 v110, v110
	v_exp_f32_e32 v111, v111
	v_mfma_f32_32x32x16_bf16 v[0:15], v[80:83], v[146:149], v[0:15]
	s_waitcnt vmcnt(8) lgkmcnt(0)
	s_barrier
	v_add_f32_e32 v186, v209, v92
	v_mfma_f32_32x32x16_bf16 v[80:95], v[68:71], v[130:133], 0
	v_add_f32_e32 v68, v114, v112
	v_add_f32_e32 v69, v115, v113
	v_cvt_pk_bf16_f32 v158, v112, v113
	v_cvt_pk_bf16_f32 v159, v114, v115
	v_add_f32_e32 v68, v116, v68
	v_add_f32_e32 v112, v117, v69
	v_add_f32_e32 v146, v118, v68
	v_cvt_pk_bf16_f32 v160, v116, v117
	v_mfma_f32_32x32x16_bf16 v[64:79], v[64:67], v[130:133], 0
	v_add_f32_e32 v116, v119, v112
	v_cvt_pk_bf16_f32 v161, v118, v119
	ds_read_b64_tr_b16 v[112:113], v207 offset:16384
	ds_read_b64_tr_b16 v[114:115], v207 offset:16896
	v_add_f32_e32 v117, v120, v146
	v_add_f32_e32 v116, v121, v116
	v_mfma_f32_32x32x16_bf16 v[80:95], v[182:185], v[134:137], v[80:95]
	v_add_f32_e32 v146, v122, v117
	v_add_f32_e32 v147, v123, v116
	v_cvt_pk_bf16_f32 v154, v120, v121
	v_cvt_pk_bf16_f32 v155, v122, v123
	ds_read_b64_tr_b16 v[116:117], v207 offset:20480
	ds_read_b64_tr_b16 v[118:119], v207 offset:20992
	v_add_f32_e32 v120, v124, v146
	v_add_f32_e32 v121, v125, v147
	v_mfma_f32_32x32x16_bf16 v[64:79], v[178:181], v[134:137], v[64:79]
	v_add_f32_e32 v146, v126, v120
	v_add_f32_e32 v147, v127, v121
	v_cvt_pk_bf16_f32 v156, v124, v125
	v_cvt_pk_bf16_f32 v157, v126, v127
	ds_read_b64_tr_b16 v[120:121], v207 offset:24576
	ds_read_b64_tr_b16 v[122:123], v207 offset:25088
	v_add_f32_e32 v124, v96, v146
	v_add_f32_e32 v125, v97, v147
	v_mfma_f32_32x32x16_bf16 v[80:95], v[174:177], v[138:141], v[80:95]
	v_add_f32_e32 v124, v98, v124
	v_add_f32_e32 v125, v99, v125
	v_cvt_pk_bf16_f32 v150, v96, v97
	v_cvt_pk_bf16_f32 v151, v98, v99
	ds_read_b64_tr_b16 v[96:97], v207 offset:28672
	ds_read_b64_tr_b16 v[98:99], v207 offset:29184
	v_add_f32_e32 v124, v100, v124
	v_add_f32_e32 v125, v101, v125
	v_mfma_f32_32x32x16_bf16 v[64:79], v[170:173], v[138:141], v[64:79]
	s_add_i32 s90, s33, 6
	s_min_u32 s90, s90, s19
	s_mul_i32 s90, s90, 0x160000
	s_add_i32 m0, s5, 0x8000
	s_add_u32 s100, s44, s90
	s_addc_u32 s101, s45, 0
	global_load_lds_dwordx4 v199, s[100:101]
	v_add_f32_e32 v124, v102, v124
	v_add_f32_e32 v125, v103, v125
	v_cvt_pk_bf16_f32 v152, v100, v101
	v_cvt_pk_bf16_f32 v153, v102, v103
	v_add_f32_e32 v100, v104, v124
	v_add_f32_e32 v101, v105, v125
	v_mfma_f32_32x32x16_bf16 v[80:95], v[166:169], v[142:145], v[80:95]
	s_add_i32 m0, s32, 0x8000
	s_nop 0
	global_load_lds_dwordx4 v199, s[100:101] offset:128
	v_add_f32_e32 v100, v106, v100
	v_add_f32_e32 v101, v107, v101
	v_cvt_pk_bf16_f32 v146, v104, v105
	v_cvt_pk_bf16_f32 v147, v106, v107
	v_add_f32_e32 v100, v108, v100
	v_add_f32_e32 v101, v109, v101
	v_mfma_f32_32x32x16_bf16 v[64:79], v[162:165], v[142:145], v[64:79]
	s_add_i32 s90, s33, 4
	s_min_u32 s90, s90, s19
	s_mul_i32 s90, s90, 0x160000
	s_add_i32 m0, s22, 0x0
	s_add_u32 s100, s44, s90
	s_addc_u32 s101, s45, 0
	global_load_lds_dwordx4 v201, s[100:101]
	v_add_f32_e32 v100, v110, v100
	v_add_f32_e32 v101, v111, v101
	v_cvt_pk_bf16_f32 v148, v108, v109
	v_cvt_pk_bf16_f32 v149, v110, v111
	v_add_f32_e32 v100, v100, v101
	v_exp_f32_e32 v80, v80
	v_exp_f32_e32 v81, v81
	s_waitcnt lgkmcnt(4)
	v_mfma_f32_32x32x16_bf16 v[48:63], v[112:115], v[158:161], v[48:63]
	v_add_f32_e32 v209, v186, v100
	ds_read_b64_tr_b16 v[100:101], v207 offset:17408
	ds_read_b64_tr_b16 v[102:103], v207 offset:17920
	v_exp_f32_e32 v82, v82
	v_exp_f32_e32 v83, v83
	v_mfma_f32_32x32x16_bf16 v[32:47], v[116:119], v[158:161], v[32:47]
	ds_read_b64_tr_b16 v[104:105], v207 offset:21504
	ds_read_b64_tr_b16 v[106:107], v207 offset:22016
	v_exp_f32_e32 v84, v84
	v_exp_f32_e32 v85, v85
	s_waitcnt lgkmcnt(4)
	v_mfma_f32_32x32x16_bf16 v[16:31], v[120:123], v[158:161], v[16:31]
	ds_read_b64_tr_b16 v[108:109], v207 offset:25600
	ds_read_b64_tr_b16 v[110:111], v207 offset:26112
	v_exp_f32_e32 v86, v86
	v_exp_f32_e32 v87, v87
	v_mfma_f32_32x32x16_bf16 v[0:15], v[96:99], v[158:161], v[0:15]
	ds_read_b64_tr_b16 v[112:113], v207 offset:29696
	ds_read_b64_tr_b16 v[114:115], v207 offset:30208
	v_exp_f32_e32 v88, v88
	v_exp_f32_e32 v89, v89
	s_waitcnt lgkmcnt(4)
	v_mfma_f32_32x32x16_bf16 v[48:63], v[100:103], v[154:157], v[48:63]
	ds_read_b64_tr_b16 v[116:117], v207 offset:18432
	ds_read_b64_tr_b16 v[118:119], v207 offset:18944
	ds_read_b128 v[100:103], v204 offset:49152
	v_exp_f32_e32 v90, v90
	v_exp_f32_e32 v91, v91
	v_mfma_f32_32x32x16_bf16 v[32:47], v[104:107], v[154:157], v[32:47]
	ds_read_b64_tr_b16 v[104:105], v207 offset:22528
	ds_read_b64_tr_b16 v[106:107], v207 offset:23040
	ds_read_b128 v[96:99], v204 offset:53248
	v_exp_f32_e32 v92, v92
	v_exp_f32_e32 v93, v93
	s_waitcnt lgkmcnt(6)
	v_mfma_f32_32x32x16_bf16 v[16:31], v[108:111], v[154:157], v[16:31]
	ds_read_b64_tr_b16 v[108:109], v207 offset:26624
	ds_read_b64_tr_b16 v[110:111], v207 offset:27136
	ds_read_b128 v[182:185], v128 offset:49152
	v_exp_f32_e32 v94, v94
	v_exp_f32_e32 v95, v95
	v_mfma_f32_32x32x16_bf16 v[0:15], v[112:115], v[154:157], v[0:15]
	ds_read_b64_tr_b16 v[112:113], v207 offset:30720
	ds_read_b64_tr_b16 v[114:115], v207 offset:31232
	ds_read_b128 v[178:181], v128 offset:53248
	v_exp_f32_e32 v64, v64
	v_exp_f32_e32 v65, v65
	s_waitcnt lgkmcnt(7)
	v_mfma_f32_32x32x16_bf16 v[48:63], v[116:119], v[150:153], v[48:63]
	ds_read_b64_tr_b16 v[116:117], v207 offset:19456
	ds_read_b64_tr_b16 v[118:119], v207 offset:19968
	ds_read_b128 v[174:177], v205 offset:49152
	v_exp_f32_e32 v66, v66
	v_exp_f32_e32 v67, v67
	v_mfma_f32_32x32x16_bf16 v[32:47], v[104:107], v[150:153], v[32:47]
	ds_read_b64_tr_b16 v[104:105], v207 offset:23552
	ds_read_b64_tr_b16 v[106:107], v207 offset:24064
	ds_read_b128 v[170:173], v205 offset:53248
	v_exp_f32_e32 v68, v68
	v_exp_f32_e32 v69, v69
	s_waitcnt lgkmcnt(7)
	v_mfma_f32_32x32x16_bf16 v[16:31], v[108:111], v[150:153], v[16:31]
	ds_read_b64_tr_b16 v[108:109], v207 offset:27648
	ds_read_b64_tr_b16 v[110:111], v207 offset:28160
	ds_read_b128 v[166:169], v206 offset:49152
	v_exp_f32_e32 v70, v70
	v_exp_f32_e32 v71, v71
	v_mfma_f32_32x32x16_bf16 v[0:15], v[112:115], v[150:153], v[0:15]
	ds_read_b64_tr_b16 v[112:113], v207 offset:31744
	ds_read_b64_tr_b16 v[114:115], v207 offset:32256
	ds_read_b128 v[162:165], v206 offset:53248
	v_exp_f32_e32 v72, v72
	v_exp_f32_e32 v73, v73
	s_waitcnt lgkmcnt(7)
	v_mfma_f32_32x32x16_bf16 v[48:63], v[116:119], v[146:149], v[48:63]
	s_add_i32 m0, s22, 0x0
	s_addk_i32 m0, 0x400
	s_add_u32 s100, s100, 0x58000
	s_addc_u32 s101, s101, 0
	global_load_lds_dwordx4 v201, s[100:101]
	v_exp_f32_e32 v74, v74
	v_exp_f32_e32 v75, v75
	v_mfma_f32_32x32x16_bf16 v[32:47], v[104:107], v[146:149], v[32:47]
	v_exp_f32_e32 v76, v76
	v_exp_f32_e32 v77, v77
	s_waitcnt lgkmcnt(1)
	v_mfma_f32_32x32x16_bf16 v[16:31], v[108:111], v[146:149], v[16:31]
	v_exp_f32_e32 v78, v78
	v_exp_f32_e32 v79, v79
	v_mfma_f32_32x32x16_bf16 v[0:15], v[112:115], v[146:149], v[0:15]
	s_waitcnt vmcnt(8) lgkmcnt(0)
	s_barrier
	s_cmp_ge_u32 s24, s4
	s_mov_b32 s33, s24
	s_cbranch_scc1 .Lattn_done
	s_add_i32 s24, s33, 2
	v_mfma_f32_32x32x16_bf16 v[112:127], v[100:103], v[130:133], 0
	v_add_f32_e32 v100, v82, v80
	v_add_f32_e32 v101, v83, v81
	v_cvt_pk_bf16_f32 v158, v80, v81
	v_cvt_pk_bf16_f32 v159, v82, v83
	v_add_f32_e32 v80, v84, v100
	v_add_f32_e32 v81, v85, v101
	v_add_f32_e32 v146, v86, v80
	v_cvt_pk_bf16_f32 v160, v84, v85
	v_mfma_f32_32x32x16_bf16 v[96:111], v[96:99], v[130:133], 0
	v_add_f32_e32 v84, v87, v81
	v_cvt_pk_bf16_f32 v161, v86, v87
	ds_read_b64_tr_b16 v[80:81], v207 offset:32768
	ds_read_b64_tr_b16 v[82:83], v207 offset:33280
	v_add_f32_e32 v85, v88, v146
	v_add_f32_e32 v84, v89, v84
	v_mfma_f32_32x32x16_bf16 v[112:127], v[182:185], v[134:137], v[112:127]
	v_add_f32_e32 v146, v90, v85
	v_add_f32_e32 v147, v91, v84
	v_cvt_pk_bf16_f32 v154, v88, v89
	v_cvt_pk_bf16_f32 v155, v90, v91
	ds_read_b64_tr_b16 v[84:85], v207 offset:36864
	ds_read_b64_tr_b16 v[86:87], v207 offset:37376
	v_add_f32_e32 v88, v92, v146
	v_add_f32_e32 v89, v93, v147
	v_mfma_f32_32x32x16_bf16 v[96:111], v[178:181], v[134:137], v[96:111]
	v_add_f32_e32 v146, v94, v88
	v_add_f32_e32 v147, v95, v89
	v_cvt_pk_bf16_f32 v156, v92, v93
	v_cvt_pk_bf16_f32 v157, v94, v95
	ds_read_b64_tr_b16 v[88:89], v207 offset:40960
	ds_read_b64_tr_b16 v[90:91], v207 offset:41472
	v_add_f32_e32 v92, v64, v146
	v_add_f32_e32 v93, v65, v147
	v_mfma_f32_32x32x16_bf16 v[112:127], v[174:177], v[138:141], v[112:127]
	v_add_f32_e32 v92, v66, v92
	v_add_f32_e32 v93, v67, v93
	v_cvt_pk_bf16_f32 v150, v64, v65
	v_cvt_pk_bf16_f32 v151, v66, v67
	ds_read_b64_tr_b16 v[64:65], v207 offset:45056
	ds_read_b64_tr_b16 v[66:67], v207 offset:45568
	v_add_f32_e32 v92, v68, v92
	v_add_f32_e32 v93, v69, v93
	v_mfma_f32_32x32x16_bf16 v[96:111], v[170:173], v[138:141], v[96:111]
	s_add_i32 s90, s33, 5
	s_min_u32 s90, s90, s19
	s_mul_i32 s90, s90, 0x160000
	s_add_i32 m0, s5, 0xc000
	s_add_u32 s100, s44, s90
	s_addc_u32 s101, s45, 0
	global_load_lds_dwordx4 v199, s[100:101]
	v_add_f32_e32 v92, v70, v92
	v_add_f32_e32 v93, v71, v93
	v_cvt_pk_bf16_f32 v152, v68, v69
	v_cvt_pk_bf16_f32 v153, v70, v71
	v_add_f32_e32 v68, v72, v92
	v_add_f32_e32 v69, v73, v93
	v_mfma_f32_32x32x16_bf16 v[112:127], v[166:169], v[142:145], v[112:127]
	s_add_i32 m0, s32, 0xc000
	s_nop 0
	global_load_lds_dwordx4 v199, s[100:101] offset:128
	v_add_f32_e32 v68, v74, v68
	v_add_f32_e32 v69, v75, v69
	v_cvt_pk_bf16_f32 v146, v72, v73
	v_cvt_pk_bf16_f32 v147, v74, v75
	v_add_f32_e32 v68, v76, v68
	v_add_f32_e32 v69, v77, v69
	v_mfma_f32_32x32x16_bf16 v[96:111], v[162:165], v[142:145], v[96:111]
	s_add_i32 s90, s33, 3
	s_min_u32 s90, s90, s19
	s_mul_i32 s90, s90, 0x160000
	s_add_i32 m0, s22, 0x4000
	s_add_u32 s100, s44, s90
	s_addc_u32 s101, s45, 0
	global_load_lds_dwordx4 v201, s[100:101]
	v_add_f32_e32 v68, v78, v68
	v_add_f32_e32 v69, v79, v69
	v_cvt_pk_bf16_f32 v148, v76, v77
	v_cvt_pk_bf16_f32 v149, v78, v79
	s_nop 0
	v_exp_f32_e32 v112, v112
	v_exp_f32_e32 v113, v113
	s_waitcnt lgkmcnt(4)
	v_mfma_f32_32x32x16_bf16 v[48:63], v[80:83], v[158:161], v[48:63]
	v_add_f32_e32 v92, v68, v69
	ds_read_b64_tr_b16 v[68:69], v207 offset:33792
	ds_read_b64_tr_b16 v[70:71], v207 offset:34304
	v_exp_f32_e32 v114, v114
	v_exp_f32_e32 v115, v115
	v_mfma_f32_32x32x16_bf16 v[32:47], v[84:87], v[158:161], v[32:47]
	ds_read_b64_tr_b16 v[72:73], v207 offset:37888
	ds_read_b64_tr_b16 v[74:75], v207 offset:38400
	v_exp_f32_e32 v116, v116
	v_exp_f32_e32 v117, v117
	s_waitcnt lgkmcnt(4)
	v_mfma_f32_32x32x16_bf16 v[16:31], v[88:91], v[158:161], v[16:31]
	ds_read_b64_tr_b16 v[76:77], v207 offset:41984
	ds_read_b64_tr_b16 v[78:79], v207 offset:42496
	v_exp_f32_e32 v118, v118
	v_exp_f32_e32 v119, v119
	v_mfma_f32_32x32x16_bf16 v[0:15], v[64:67], v[158:161], v[0:15]
	ds_read_b64_tr_b16 v[80:81], v207 offset:46080
	ds_read_b64_tr_b16 v[82:83], v207 offset:46592
	v_exp_f32_e32 v120, v120
	v_exp_f32_e32 v121, v121
	s_waitcnt lgkmcnt(4)
	v_mfma_f32_32x32x16_bf16 v[48:63], v[68:71], v[154:157], v[48:63]
	ds_read_b64_tr_b16 v[84:85], v207 offset:34816
	ds_read_b64_tr_b16 v[86:87], v207 offset:35328
	ds_read_b128 v[68:71], v204
	v_exp_f32_e32 v122, v122
	v_exp_f32_e32 v123, v123
	v_mfma_f32_32x32x16_bf16 v[32:47], v[72:75], v[154:157], v[32:47]
	ds_read_b64_tr_b16 v[72:73], v207 offset:38912
	ds_read_b64_tr_b16 v[74:75], v207 offset:39424
	ds_read_b128 v[64:67], v204 offset:4096
	v_exp_f32_e32 v124, v124
	v_exp_f32_e32 v125, v125
	s_waitcnt lgkmcnt(6)
	v_mfma_f32_32x32x16_bf16 v[16:31], v[76:79], v[154:157], v[16:31]
	ds_read_b64_tr_b16 v[76:77], v207 offset:43008
	ds_read_b64_tr_b16 v[78:79], v207 offset:43520
	ds_read_b128 v[182:185], v128
	v_exp_f32_e32 v126, v126
	v_exp_f32_e32 v127, v127
	v_mfma_f32_32x32x16_bf16 v[0:15], v[80:83], v[154:157], v[0:15]
	ds_read_b64_tr_b16 v[80:81], v207 offset:47104
	ds_read_b64_tr_b16 v[82:83], v207 offset:47616
	ds_read_b128 v[178:181], v128 offset:4096
	v_exp_f32_e32 v96, v96
	v_exp_f32_e32 v97, v97
	s_waitcnt lgkmcnt(7)
	v_mfma_f32_32x32x16_bf16 v[48:63], v[84:87], v[150:153], v[48:63]
	ds_read_b64_tr_b16 v[84:85], v207 offset:35840
	ds_read_b64_tr_b16 v[86:87], v207 offset:36352
	ds_read_b128 v[174:177], v205
	v_exp_f32_e32 v98, v98
	v_exp_f32_e32 v99, v99
	v_mfma_f32_32x32x16_bf16 v[32:47], v[72:75], v[150:153], v[32:47]
	ds_read_b64_tr_b16 v[72:73], v207 offset:39936
	ds_read_b64_tr_b16 v[74:75], v207 offset:40448
	ds_read_b128 v[170:173], v205 offset:4096
	v_exp_f32_e32 v100, v100
	v_exp_f32_e32 v101, v101
	s_waitcnt lgkmcnt(7)
	v_mfma_f32_32x32x16_bf16 v[16:31], v[76:79], v[150:153], v[16:31]
	ds_read_b64_tr_b16 v[76:77], v207 offset:44032
	ds_read_b64_tr_b16 v[78:79], v207 offset:44544
	ds_read_b128 v[166:169], v206
	v_exp_f32_e32 v102, v102
	v_exp_f32_e32 v103, v103
	v_mfma_f32_32x32x16_bf16 v[0:15], v[80:83], v[150:153], v[0:15]
	ds_read_b64_tr_b16 v[80:81], v207 offset:48128
	ds_read_b64_tr_b16 v[82:83], v207 offset:48640
	ds_read_b128 v[162:165], v206 offset:4096
	v_exp_f32_e32 v104, v104
	v_exp_f32_e32 v105, v105
	s_waitcnt lgkmcnt(7)
	v_mfma_f32_32x32x16_bf16 v[48:63], v[84:87], v[146:149], v[48:63]
	s_add_i32 m0, s22, 0x4000
	s_addk_i32 m0, 0x400
	s_add_u32 s100, s100, 0x58000
	s_addc_u32 s101, s101, 0
	global_load_lds_dwordx4 v201, s[100:101]
	v_exp_f32_e32 v106, v106
	v_exp_f32_e32 v107, v107
	v_mfma_f32_32x32x16_bf16 v[32:47], v[72:75], v[146:149], v[32:47]
	v_exp_f32_e32 v108, v108
	v_exp_f32_e32 v109, v109
	s_waitcnt lgkmcnt(1)
	v_mfma_f32_32x32x16_bf16 v[16:31], v[76:79], v[146:149], v[16:31]
	v_exp_f32_e32 v110, v110
	v_exp_f32_e32 v111, v111
	v_mfma_f32_32x32x16_bf16 v[0:15], v[80:83], v[146:149], v[0:15]
	s_waitcnt vmcnt(8) lgkmcnt(0)
	s_barrier
	v_add_f32_e32 v186, v209, v92
	v_mfma_f32_32x32x16_bf16 v[80:95], v[68:71], v[130:133], 0
	v_add_f32_e32 v68, v114, v112
	v_add_f32_e32 v69, v115, v113
	v_cvt_pk_bf16_f32 v158, v112, v113
	v_cvt_pk_bf16_f32 v159, v114, v115
	v_add_f32_e32 v68, v116, v68
	v_add_f32_e32 v112, v117, v69
	v_add_f32_e32 v146, v118, v68
	v_cvt_pk_bf16_f32 v160, v116, v117
	v_mfma_f32_32x32x16_bf16 v[64:79], v[64:67], v[130:133], 0
	v_add_f32_e32 v116, v119, v112
	v_cvt_pk_bf16_f32 v161, v118, v119
	ds_read_b64_tr_b16 v[112:113], v207 offset:49152
	ds_read_b64_tr_b16 v[114:115], v207 offset:49664
	v_add_f32_e32 v117, v120, v146
	v_add_f32_e32 v116, v121, v116
	v_mfma_f32_32x32x16_bf16 v[80:95], v[182:185], v[134:137], v[80:95]
	v_add_f32_e32 v146, v122, v117
	v_add_f32_e32 v147, v123, v116
	v_cvt_pk_bf16_f32 v154, v120, v121
	v_cvt_pk_bf16_f32 v155, v122, v123
	ds_read_b64_tr_b16 v[116:117], v207 offset:53248
	ds_read_b64_tr_b16 v[118:119], v207 offset:53760
	v_add_f32_e32 v120, v124, v146
	v_add_f32_e32 v121, v125, v147
	v_mfma_f32_32x32x16_bf16 v[64:79], v[178:181], v[134:137], v[64:79]
	v_add_f32_e32 v146, v126, v120
	v_add_f32_e32 v147, v127, v121
	v_cvt_pk_bf16_f32 v156, v124, v125
	v_cvt_pk_bf16_f32 v157, v126, v127
	ds_read_b64_tr_b16 v[120:121], v207 offset:57344
	ds_read_b64_tr_b16 v[122:123], v207 offset:57856
	v_add_f32_e32 v124, v96, v146
	v_add_f32_e32 v125, v97, v147
	v_mfma_f32_32x32x16_bf16 v[80:95], v[174:177], v[138:141], v[80:95]
	v_add_f32_e32 v124, v98, v124
	v_add_f32_e32 v125, v99, v125
	v_cvt_pk_bf16_f32 v150, v96, v97
	v_cvt_pk_bf16_f32 v151, v98, v99
	ds_read_b64_tr_b16 v[96:97], v207 offset:61440
	ds_read_b64_tr_b16 v[98:99], v207 offset:61952
	v_add_f32_e32 v124, v100, v124
	v_add_f32_e32 v125, v101, v125
	v_mfma_f32_32x32x16_bf16 v[64:79], v[170:173], v[138:141], v[64:79]
	s_add_i32 s90, s33, 6
	s_min_u32 s90, s90, s19
	s_mul_i32 s90, s90, 0x160000
	s_add_i32 m0, s5, 0x0
	s_add_u32 s100, s44, s90
	s_addc_u32 s101, s45, 0
	global_load_lds_dwordx4 v199, s[100:101]
	v_add_f32_e32 v124, v102, v124
	v_add_f32_e32 v125, v103, v125
	v_cvt_pk_bf16_f32 v152, v100, v101
	v_cvt_pk_bf16_f32 v153, v102, v103
	v_add_f32_e32 v100, v104, v124
	v_add_f32_e32 v101, v105, v125
	v_mfma_f32_32x32x16_bf16 v[80:95], v[166:169], v[142:145], v[80:95]
	s_add_i32 m0, s32, 0x0
	s_nop 0
	global_load_lds_dwordx4 v199, s[100:101] offset:128
	v_add_f32_e32 v100, v106, v100
	v_add_f32_e32 v101, v107, v101
	v_cvt_pk_bf16_f32 v146, v104, v105
	v_cvt_pk_bf16_f32 v147, v106, v107
	v_add_f32_e32 v100, v108, v100
	v_add_f32_e32 v101, v109, v101
	v_mfma_f32_32x32x16_bf16 v[64:79], v[162:165], v[142:145], v[64:79]
	s_add_i32 s90, s33, 4
	s_min_u32 s90, s90, s19
	s_mul_i32 s90, s90, 0x160000
	s_add_i32 m0, s22, 0x8000
	s_add_u32 s100, s44, s90
	s_addc_u32 s101, s45, 0
	global_load_lds_dwordx4 v201, s[100:101]
	v_add_f32_e32 v100, v110, v100
	v_add_f32_e32 v101, v111, v101
	v_cvt_pk_bf16_f32 v148, v108, v109
	v_cvt_pk_bf16_f32 v149, v110, v111
	v_add_f32_e32 v100, v100, v101
	v_exp_f32_e32 v80, v80
	v_exp_f32_e32 v81, v81
	s_waitcnt lgkmcnt(4)
	v_mfma_f32_32x32x16_bf16 v[48:63], v[112:115], v[158:161], v[48:63]
	v_add_f32_e32 v209, v186, v100
	ds_read_b64_tr_b16 v[100:101], v207 offset:50176
	ds_read_b64_tr_b16 v[102:103], v207 offset:50688
	v_exp_f32_e32 v82, v82
	v_exp_f32_e32 v83, v83
	v_mfma_f32_32x32x16_bf16 v[32:47], v[116:119], v[158:161], v[32:47]
	ds_read_b64_tr_b16 v[104:105], v207 offset:54272
	ds_read_b64_tr_b16 v[106:107], v207 offset:54784
	v_exp_f32_e32 v84, v84
	v_exp_f32_e32 v85, v85
	s_waitcnt lgkmcnt(4)
	v_mfma_f32_32x32x16_bf16 v[16:31], v[120:123], v[158:161], v[16:31]
	ds_read_b64_tr_b16 v[108:109], v207 offset:58368
	ds_read_b64_tr_b16 v[110:111], v207 offset:58880
	v_exp_f32_e32 v86, v86
	v_exp_f32_e32 v87, v87
	v_mfma_f32_32x32x16_bf16 v[0:15], v[96:99], v[158:161], v[0:15]
	ds_read_b64_tr_b16 v[112:113], v207 offset:62464
	ds_read_b64_tr_b16 v[114:115], v207 offset:62976
	v_exp_f32_e32 v88, v88
	v_exp_f32_e32 v89, v89
	s_waitcnt lgkmcnt(4)
	v_mfma_f32_32x32x16_bf16 v[48:63], v[100:103], v[154:157], v[48:63]
	ds_read_b64_tr_b16 v[116:117], v207 offset:51200
	ds_read_b64_tr_b16 v[118:119], v207 offset:51712
	ds_read_b128 v[100:103], v204 offset:16384
	v_exp_f32_e32 v90, v90
	v_exp_f32_e32 v91, v91
	v_mfma_f32_32x32x16_bf16 v[32:47], v[104:107], v[154:157], v[32:47]
	ds_read_b64_tr_b16 v[104:105], v207 offset:55296
	ds_read_b64_tr_b16 v[106:107], v207 offset:55808
	ds_read_b128 v[96:99], v204 offset:20480
	v_exp_f32_e32 v92, v92
	v_exp_f32_e32 v93, v93
	s_waitcnt lgkmcnt(6)
	v_mfma_f32_32x32x16_bf16 v[16:31], v[108:111], v[154:157], v[16:31]
	ds_read_b64_tr_b16 v[108:109], v207 offset:59392
	ds_read_b64_tr_b16 v[110:111], v207 offset:59904
	ds_read_b128 v[182:185], v128 offset:16384
	v_exp_f32_e32 v94, v94
	v_exp_f32_e32 v95, v95
	v_mfma_f32_32x32x16_bf16 v[0:15], v[112:115], v[154:157], v[0:15]
	ds_read_b64_tr_b16 v[112:113], v207 offset:63488
	ds_read_b64_tr_b16 v[114:115], v207 offset:64000
	ds_read_b128 v[178:181], v128 offset:20480
	v_exp_f32_e32 v64, v64
	v_exp_f32_e32 v65, v65
	s_waitcnt lgkmcnt(7)
	v_mfma_f32_32x32x16_bf16 v[48:63], v[116:119], v[150:153], v[48:63]
	ds_read_b64_tr_b16 v[116:117], v207 offset:52224
	ds_read_b64_tr_b16 v[118:119], v207 offset:52736
	ds_read_b128 v[174:177], v205 offset:16384
	v_exp_f32_e32 v66, v66
	v_exp_f32_e32 v67, v67
	v_mfma_f32_32x32x16_bf16 v[32:47], v[104:107], v[150:153], v[32:47]
	ds_read_b64_tr_b16 v[104:105], v207 offset:56320
	ds_read_b64_tr_b16 v[106:107], v207 offset:56832
	ds_read_b128 v[170:173], v205 offset:20480
	v_exp_f32_e32 v68, v68
	v_exp_f32_e32 v69, v69
	s_waitcnt lgkmcnt(7)
	v_mfma_f32_32x32x16_bf16 v[16:31], v[108:111], v[150:153], v[16:31]
	ds_read_b64_tr_b16 v[108:109], v207 offset:60416
	ds_read_b64_tr_b16 v[110:111], v207 offset:60928
	ds_read_b128 v[166:169], v206 offset:16384
	v_exp_f32_e32 v70, v70
	v_exp_f32_e32 v71, v71
	v_mfma_f32_32x32x16_bf16 v[0:15], v[112:115], v[150:153], v[0:15]
	ds_read_b64_tr_b16 v[112:113], v207 offset:64512
	ds_read_b64_tr_b16 v[114:115], v207 offset:65024
	ds_read_b128 v[162:165], v206 offset:20480
	v_exp_f32_e32 v72, v72
	v_exp_f32_e32 v73, v73
	s_waitcnt lgkmcnt(7)
	v_mfma_f32_32x32x16_bf16 v[48:63], v[116:119], v[146:149], v[48:63]
	s_add_i32 m0, s22, 0x8000
	s_addk_i32 m0, 0x400
	s_add_u32 s100, s100, 0x58000
	s_addc_u32 s101, s101, 0
	global_load_lds_dwordx4 v201, s[100:101]
	v_exp_f32_e32 v74, v74
	v_exp_f32_e32 v75, v75
	v_mfma_f32_32x32x16_bf16 v[32:47], v[104:107], v[146:149], v[32:47]
	v_exp_f32_e32 v76, v76
	v_exp_f32_e32 v77, v77
	s_waitcnt lgkmcnt(1)
	v_mfma_f32_32x32x16_bf16 v[16:31], v[108:111], v[146:149], v[16:31]
	v_exp_f32_e32 v78, v78
	v_exp_f32_e32 v79, v79
	v_mfma_f32_32x32x16_bf16 v[0:15], v[112:115], v[146:149], v[0:15]
	s_waitcnt vmcnt(8) lgkmcnt(0)
	s_barrier
	s_cmp_ge_u32 s24, s4
	s_mov_b32 s33, s24
	s_cbranch_scc0 .LBB0_86
